# code warming at barriers extended from 8 KB to 16 KB of the next phase's code
# baseline (speedup 1.0000x reference)
; __device__ __forceinline__ unsigned xb_ld(unsigned* p)              { return __hip_atomic_load(p, __ATOMIC_RELAXED, __HIP_MEMORY_SCOPE_AGENT); }
; __device__ __forceinline__ unsigned xb_add(unsigned* p, unsigned v) { return __hip_atomic_fetch_add(p, v, __ATOMIC_RELAXED, __HIP_MEMORY_SCOPE_AGENT); }
; #define XB_SPIN(cond, bar) do { unsigned _sp = 0; while (cond) { __builtin_amdgcn_s_sleep(1); \
;     if ((++_sp & 255u) == 0u) { if (xb_ld(&(bar)[XB_TMO])) break; if (_sp > XB_SPIN_CAP) { atomicAdd(&(bar)[XB_TMO], 1u); break; } } } } while (0)
; __device__ __forceinline__ void xcd_barrier(const XcdBarrier& b) {
;     asm volatile("s_waitcnt vmcnt(0)" ::: "memory");
;     __syncthreads();
;     if (threadIdx.x == 0) {
;         unsigned* bar = b.bar;
;         __builtin_amdgcn_s_waitcnt(0);
;         unsigned nloc = b.st[0], nx = b.st[1];
;         if (nloc == 0u) { xcd_barrier_complete(bar, b.x, nloc, nx); b.st[0] = nloc; b.st[1] = nx; }
;         const unsigned old = xb_add(&bar[XB_XSUB(b.x)], 1u);
;         const unsigned gen = old / nloc;
;         if (old + 1u == (gen + 1u) * nloc) {
;             __builtin_amdgcn_fence(__ATOMIC_RELEASE, "agent");
;             asm volatile("s_waitcnt vmcnt(0)" ::: "memory");
;             const unsigned og = xb_add(&bar[XB_TOP], 1u);
;             const unsigned tg = og / nx;
;             if (og + 1u == (tg + 1u) * nx) xb_add(&bar[XB_TOPGEN], 1u);
;             else XB_SPIN(xb_ld(&bar[XB_TOPGEN]) == tg, bar);
;             __builtin_amdgcn_fence(__ATOMIC_ACQUIRE, "agent");
;             xb_add(&bar[XB_XGEN(b.x)], 1u);
;             asm volatile("s_waitcnt vmcnt(0)" ::: "memory");
;         } else {
;             XB_SPIN(xb_ld(&bar[XB_XGEN(b.x)]) == gen, bar);
;             __builtin_amdgcn_fence(__ATOMIC_ACQUIRE, "agent");
;             asm volatile("s_waitcnt vmcnt(0)" ::: "memory");
;         }
;     }
;     __syncthreads();
.Lwarm_loop_0:
	s_mov_b32 m0, s8
	s_nop 0
	global_load_lds_dwordx4 v[0:1], off
	v_lshl_add_u64 v[0:1], v[0:1], 0, s[2:3]
	s_add_u32 s8, s8, 0x400
	s_cmp_lt_u32 s8, 0x4000
	s_cbranch_scc1 .Lwarm_loop_0
	s_waitcnt vmcnt(0)
